# baseline (speedup 1.0000x reference)
; #define LAS __attribute__((address_space(3)))
; template <bool PASS2>
; __device__ __forceinline__ void ssm_fast_item(const Ctx& C, int item) {
;     const int lane = C.lane, l32 = lane & 31, hf = lane >> 5;
;     const int ch = (item & 2048) ? (NCH - 1) - (item & (NCH - 1)) : (item & (NCH - 1)), g = (item >> 5) & 31, b = item >> 10;
;     LAS unsigned* shw = (LAS unsigned*)C.lds + C.wave * SSM_WAVE_FLOATS;
;     const bf16* PROJ = WSP(const bf16, WS_PROJ);
;     const float ar = WSP(const float, WS_ABAR)[2 * (g * 64 + lane)], ai = WSP(const float, WS_ABAR)[2 * (g * 64 + lane) + 1];
;     bf16x8 bfr[4];
; #pragma unroll
;     for (int nb = 0; nb < 4; ++nb) {
;         const int col = 32 * nb + l32;
;         const float* src = (col < 64 ? WSP(const float, WS_BBRE) + (size_t)(g * 64 + col) * 16 : WSP(const float, WS_BBIM) + (size_t)(g * 64 + col - 64) * 16) + 8 * hf;
;         const f32x4 x0 = *(const f32x4*)src, x1 = *(const f32x4*)(src + 4);
;         bfr[nb] = pack8(x0.x, x0.y, x0.z, x0.w, x1.x, x1.y, x1.z, x1.w);
;     }
;     bf16x8 cfr[8];
;     if (PASS2) {
; #pragma unroll
;         for (int kk = 0; kk < 8; ++kk) {
;             f32x4 cr = {0.f, 0.f, 0.f, 0.f}, ci = cr;
;             if (l32 < 16) { cr = *(const f32x4*)(C.in[9] + (size_t)(g * 16 + l32) * 64 + 8 * kk + 4 * hf); ci = *(const f32x4*)(C.in[10] + (size_t)(g * 16 + l32) * 64 + 8 * kk + 4 * hf); }
.LBB0_445:
	s_or_b64 exec, exec, s[4:5]
	s_andn2_b64 vcc, exec, s[0:1]
	v_and_b32_e32 v201, 31, v182
	s_cbranch_vccnz .LBB0_477
	v_mov_b32_e32 v129, 0
	v_and_b32_e32 v0, 32, v196
	v_mov_b32_e32 v1, v129
	s_mul_i32 s4, s90, 0x4200
	s_add_u32 s0, s78, 0x1a400000
	v_lshl_add_u64 v[0:1], s[78:79], 0, v[0:1]
	s_mov_b64 s[2:3], 0x1a410000
	v_lshrrev_b32_e32 v3, 5, v196
	s_addc_u32 s1, s79, 0
	v_lshl_add_u64 v[130:131], v[0:1], 0, s[2:3]
	s_add_i32 s2, s4, 0
	v_lshlrev_b32_e32 v6, 2, v196
	v_lshlrev_b32_e32 v2, 2, v3
	v_mov_b32_e32 v7, s2
	s_waitcnt vmcnt(2)
	v_lshl_add_u32 v8, v201, 2, s2
	v_add_u32_e32 v141, s2, v6
	s_movk_i32 s2, 0x110
	v_lshlrev_b32_e32 v128, 3, v3
	s_add_u32 s4, s78, 0x1a404000
	v_mad_u32_u24 v9, v201, s2, v7
	v_or_b32_e32 v7, 8, v2
	s_mov_b64 s[8:9], 0x1a430000
	s_addc_u32 s5, s79, 0
	v_mul_u32_u24_e32 v10, 0x110, v7
	v_lshl_add_u64 v[146:147], v[0:1], 0, s[8:9]
	v_lshl_add_u64 v[0:1], s[78:79], 0, v[128:129]
	s_mov_b64 s[8:9], 0x12000000
	v_mov_b32_e32 v7, v129
	v_lshlrev_b32_e32 v4, 4, v3
	v_mov_b32_e32 v5, v129
	v_mul_u32_u24_e32 v3, 0x440, v3
	v_lshl_add_u64 v[148:149], v[0:1], 0, s[8:9]
	v_lshl_add_u64 v[0:1], s[78:79], 0, v[6:7]
	s_mov_b64 s[8:9], 0x1a500700
	s_add_u32 s7, s78, 0x1a500100
	v_or_b32_e32 v137, 32, v201
	s_mov_b32 s3, 0
	v_cmp_gt_u32_e32 vcc, 16, v201
	v_lshlrev_b32_e32 v139, 6, v201
	v_lshl_add_u64 v[132:133], s[10:11], 0, v[4:5]
	v_lshl_add_u64 v[134:135], s[12:13], 0, v[4:5]
	v_lshl_add_u64 v[144:145], s[14:15], 0, v[4:5]
	v_lshl_add_u64 v[150:151], v[0:1], 0, s[8:9]
	s_addc_u32 s16, s79, 0
	s_mov_b64 s[8:9], 0x800
	s_mov_b64 s[10:11], 0x200
	v_lshlrev_b32_e32 v152, 1, v128
	v_lshlrev_b32_e32 v154, 1, v2
	v_add_u32_e32 v143, v8, v3
	v_add_u32_e32 v177, v8, v10
	v_add_u32_e32 v178, v9, v4
	v_readfirstlane_b32 s27, v182
	s_nop 3
	s_lshr_b32 s27, s27, 6
	s_cmp_lt_u32 s27, 4
	s_cbranch_scc1 .Lstag_ssm2
	s_sleep 19
.Lstag_ssm2:
.LBB0_447:
	s_bfe_u32 s2, s6, 0x50005
	s_lshl_b32 s12, s2, 6
	v_or_b32_e32 v100, s12, v196
	v_or_b32_e32 v0, s12, v201
	v_lshlrev_b32_e32 v6, 3, v100
	v_lshlrev_b32_e32 v128, 6, v0
	v_lshl_add_u64 v[4:5], v[130:131], 0, v[128:129]
	global_load_dwordx2 v[156:157], v6, s[0:1]
	global_load_dwordx4 v[0:3], v[4:5], off
	v_or_b32_e32 v6, s12, v137
	v_lshlrev_b32_e32 v6, 6, v6
	v_mov_b32_e32 v7, v129
	v_lshl_add_u64 v[32:33], v[130:131], 0, v[6:7]
	global_load_dwordx4 v[8:11], v[4:5], off offset:16
	global_load_dwordx4 v[12:15], v[32:33], off
	v_lshl_add_u64 v[34:35], v[146:147], 0, v[128:129]
	global_load_dwordx4 v[20:23], v[32:33], off offset:16
	global_load_dwordx4 v[28:31], v[34:35], off
	global_load_dwordx4 v[4:7], v[34:35], off offset:2064
	global_load_dwordx4 v[24:27], v[34:35], off offset:16
	global_load_dwordx4 v[16:19], v[34:35], off offset:2048
	s_lshl_b32 s13, s2, 10
	v_add_lshl_u32 v128, v139, s13, 2
	v_lshl_add_u64 v[96:97], v[132:133], 0, v[128:129]
	v_lshl_add_u64 v[98:99], v[134:135], 0, v[128:129]
	v_mov_b32_e32 v36, 0
	v_mov_b32_e32 v37, 0
	v_mov_b32_e32 v38, 0
	v_mov_b32_e32 v39, 0
	v_mov_b32_e32 v32, 0
	v_mov_b32_e32 v33, 0
	v_mov_b32_e32 v34, 0
	v_mov_b32_e32 v35, 0
	s_and_saveexec_b64 s[14:15], vcc
	s_cbranch_execz .LBB0_449
	global_load_dwordx4 v[32:35], v[96:97], off
	global_load_dwordx4 v[36:39], v[98:99], off
